# latent attention: QK^T-section VALU (exp/sum/cvt/permlane) re-spaced evenly across the 16 MFMA gaps by a dependency-checked list scheduler
# baseline (speedup 1.0000x reference)
.LBB0_709:
	s_add_i32 s20, s85, -3
	ds_read_b128 v[64:67], v204 offset:49152
	ds_read_b128 v[68:71], v204 offset:57344
	ds_read_b128 v[178:181], v207 offset:49152
	ds_read_b128 v[182:185], v207 offset:57344
	s_waitcnt lgkmcnt(3)
	v_mfma_f32_32x32x16_bf16 v[80:95], v[64:67], v[124:127], 0
	v_exp_f32_e32 v144, v158
	v_exp_f32_e32 v158, v159
	v_cvt_pk_bf16_f32 v162, v173, v175
	s_waitcnt lgkmcnt(2)
	v_mfma_f32_32x32x16_bf16 v[64:79], v[68:71], v[124:127], 0
	v_exp_f32_e32 v159, v160
	v_add_f32_e32 v160, 0, v216
	v_add_f32_e32 v160, v230, v160
	v_add_f32_e32 v160, v174, v160
	v_add_f32_e32 v160, v219, v160
	s_waitcnt lgkmcnt(1)
	v_mfma_f32_32x32x16_bf16 v[80:95], v[178:181], v[120:123], v[80:95]
	v_add_f32_e32 v160, v173, v160
	v_add_f32_e32 v160, v175, v160
	v_add_f32_e32 v160, v163, v160
	v_add_f32_e32 v160, v172, v160
	v_add_f32_e32 v160, v164, v160
	s_waitcnt lgkmcnt(0)
	v_mfma_f32_32x32x16_bf16 v[64:79], v[182:185], v[120:123], v[64:79]
	v_add_f32_e32 v160, v171, v160
	v_add_f32_e32 v160, v165, v160
	v_add_f32_e32 v160, v170, v160
	v_add_f32_e32 v160, v166, v160
	v_add_f32_e32 v160, v169, v160
	ds_read_b128 v[178:181], v209 offset:49152
	ds_read_b128 v[182:185], v209 offset:57344
	s_waitcnt lgkmcnt(1)
	v_mfma_f32_32x32x16_bf16 v[80:95], v[178:181], v[116:119], v[80:95]
	v_exp_f32_e32 v156, v156
	v_add_f32_e32 v160, v145, v160
	v_exp_f32_e32 v157, v157
	v_add_f32_e32 v160, v167, v160
	v_add_f32_e32 v160, v144, v160
	s_waitcnt lgkmcnt(0)
	v_mfma_f32_32x32x16_bf16 v[64:79], v[182:185], v[116:119], v[64:79]
	v_exp_f32_e32 v150, v150
	v_exp_f32_e32 v151, v151
	v_add_f32_e32 v160, v158, v160
	v_add_f32_e32 v160, v156, v160
	v_add_f32_e32 v160, v157, v160
	ds_read_b128 v[178:181], v205 offset:49152
	ds_read_b128 v[182:185], v205 offset:57344
	s_waitcnt lgkmcnt(1)
	v_mfma_f32_32x32x16_bf16 v[80:95], v[178:181], v[112:115], v[80:95]
	v_exp_f32_e32 v148, v148
	v_exp_f32_e32 v149, v149
	v_add_f32_e32 v160, v150, v160
	v_add_f32_e32 v160, v151, v160
	v_add_f32_e32 v160, v148, v160
	s_waitcnt lgkmcnt(0)
	v_mfma_f32_32x32x16_bf16 v[64:79], v[182:185], v[112:115], v[64:79]
	v_exp_f32_e32 v146, v146
	v_exp_f32_e32 v147, v147
	v_add_f32_e32 v160, v149, v160
	v_add_f32_e32 v160, v146, v160
	v_add_f32_e32 v160, v147, v160
	ds_read_b128 v[178:181], v206 offset:49152
	ds_read_b128 v[182:185], v206 offset:57344
	s_waitcnt lgkmcnt(1)
	v_mfma_f32_32x32x16_bf16 v[80:95], v[178:181], v[108:111], v[80:95]
	v_exp_f32_e32 v154, v154
	v_exp_f32_e32 v155, v155
	v_add_f32_e32 v160, v159, v160
	v_cvt_pk_bf16_f32 v163, v163, v172
	v_cvt_pk_bf16_f32 v164, v164, v171
	s_waitcnt lgkmcnt(0)
	v_mfma_f32_32x32x16_bf16 v[64:79], v[182:185], v[108:111], v[64:79]
	v_exp_f32_e32 v152, v152
	v_exp_f32_e32 v153, v153
	v_cvt_pk_bf16_f32 v165, v165, v170
	v_cvt_pk_bf16_f32 v166, v166, v169
	v_cvt_pk_bf16_f32 v167, v145, v167
	ds_read_b128 v[178:181], v208 offset:49152
	ds_read_b128 v[182:185], v208 offset:57344
	s_waitcnt lgkmcnt(1)
	v_mfma_f32_32x32x16_bf16 v[80:95], v[178:181], v[104:107], v[80:95]
	v_cvt_pk_bf16_f32 v170, v144, v158
	v_cvt_pk_bf16_f32 v171, v156, v157
	v_cvt_pk_bf16_f32 v172, v150, v151
	v_cvt_pk_bf16_f32 v173, v148, v149
	v_permlane32_swap_b32_e32 v164, v166
	s_waitcnt lgkmcnt(0)
	v_mfma_f32_32x32x16_bf16 v[64:79], v[182:185], v[104:107], v[64:79]
	v_permlane32_swap_b32_e32 v165, v167
	v_permlane32_swap_b32_e32 v170, v172
	v_permlane32_swap_b32_e32 v171, v173
	ds_read_b128 v[178:181], v210 offset:49152
	ds_read_b128 v[182:185], v210 offset:57344
	s_waitcnt lgkmcnt(1)
	v_mfma_f32_32x32x16_bf16 v[80:95], v[178:181], v[100:103], v[80:95]
	s_waitcnt lgkmcnt(0)
	v_mfma_f32_32x32x16_bf16 v[64:79], v[182:185], v[100:103], v[64:79]
	ds_read_b128 v[178:181], v211 offset:49152
	ds_read_b128 v[182:185], v211 offset:57344
	s_waitcnt lgkmcnt(1)
	v_mfma_f32_32x32x16_bf16 v[80:95], v[178:181], v[96:99], v[80:95]
	v_exp_f32_e32 v179, v161
	s_nop 0
	v_add_f32_e32 v160, v179, v160
	v_add_f32_e32 v160, v154, v160
	v_add_f32_e32 v160, v155, v160
	v_add_f32_e32 v160, v152, v160
	s_waitcnt lgkmcnt(0)
	v_mfma_f32_32x32x16_bf16 v[64:79], v[182:185], v[96:99], v[64:79]
	v_add_f32_e32 v213, v153, v160
	v_mov_b32_e32 v214, v213
	v_cvt_pk_bf16_f32 v160, v216, v230
	v_cvt_pk_bf16_f32 v161, v174, v219
	v_permlane32_swap_b32_e32 v213, v214
	v_permlane32_swap_b32_e32 v160, v162
	v_cvt_pk_bf16_f32 v178, v146, v147
	v_cvt_pk_bf16_f32 v179, v159, v179
	v_cvt_pk_bf16_f32 v180, v154, v155
	v_cvt_pk_bf16_f32 v181, v152, v153
	v_permlane32_swap_b32_e32 v161, v163
	v_permlane32_swap_b32_e32 v178, v180
	v_permlane32_swap_b32_e32 v179, v181
	s_cmp_lt_u32 s20, 6
	s_cselect_b64 s[4:5], -1, 0
	s_and_b64 s[18:19], s[4:5], exec
	s_cselect_b32 s16, 0, -8
	s_add_i32 s16, s16, s85
	s_add_i32 s16, s16, -1
	s_and_b64 s[4:5], s[4:5], exec
	s_cselect_b32 s19, s49, s43
	s_cselect_b32 s18, s48, s36
	s_cselect_b32 s21, s57, s52
	s_cselect_b32 s22, s56, s44
	s_lshl_b64 s[4:5], s[16:17], 16
	s_add_u32 s18, s18, s4
	s_addc_u32 s19, s19, s5
	s_add_u32 s4, s22, s4
	s_addc_u32 s5, s21, s5
	global_load_dwordx4 v[144:147], v222, s[4:5]
	global_load_dwordx4 v[148:151], v243, s[4:5]
	global_load_dwordx4 v[152:155], v222, s[18:19]
	global_load_dwordx4 v[156:159], v243, s[18:19]
	ds_read_b64_tr_b16 v[182:183], v199 offset:0
	ds_read_b64_tr_b16 v[184:185], v199 offset:0x800
	ds_read_b64_tr_b16 v[216:217], v199 offset:0x1000
	ds_read_b64_tr_b16 v[218:219], v199 offset:0x1800
	ds_read_b64_tr_b16 v[230:231], v199 offset:0x2000
	ds_read_b64_tr_b16 v[232:233], v199 offset:0x2800
	ds_read_b64_tr_b16 v[234:235], v199 offset:0x3000
	ds_read_b64_tr_b16 v[236:237], v199 offset:0x3800
	s_waitcnt lgkmcnt(0)
	s_nop 0
	v_mfma_f32_32x32x16_bf16 v[0:15], v[160:163], v[182:185], v[0:15]
	ds_read_b64_tr_b16 v[182:183], v199 offset:0x200
	ds_read_b64_tr_b16 v[184:185], v199 offset:0xa00
	v_mfma_f32_32x32x16_bf16 v[0:15], v[164:167], v[216:219], v[0:15]
	ds_read_b64_tr_b16 v[216:217], v199 offset:0x1200
	ds_read_b64_tr_b16 v[218:219], v199 offset:0x1a00
	v_mfma_f32_32x32x16_bf16 v[0:15], v[170:173], v[230:233], v[0:15]
	ds_read_b64_tr_b16 v[230:231], v199 offset:0x2200
	ds_read_b64_tr_b16 v[232:233], v199 offset:0x2a00
	v_mfma_f32_32x32x16_bf16 v[0:15], v[178:181], v[234:237], v[0:15]
	ds_read_b64_tr_b16 v[234:235], v199 offset:0x3200
	ds_read_b64_tr_b16 v[236:237], v199 offset:0x3a00
	s_waitcnt lgkmcnt(0)
	v_mfma_f32_32x32x16_bf16 v[48:63], v[160:163], v[182:185], v[48:63]
	ds_read_b64_tr_b16 v[182:183], v199 offset:0x400
	ds_read_b64_tr_b16 v[184:185], v199 offset:0xc00
	v_mfma_f32_32x32x16_bf16 v[48:63], v[164:167], v[216:219], v[48:63]
	ds_read_b64_tr_b16 v[216:217], v199 offset:0x1400
	ds_read_b64_tr_b16 v[218:219], v199 offset:0x1c00
	v_mfma_f32_32x32x16_bf16 v[48:63], v[170:173], v[230:233], v[48:63]
	ds_read_b64_tr_b16 v[230:231], v199 offset:0x2400
	ds_read_b64_tr_b16 v[232:233], v199 offset:0x2c00
	v_mfma_f32_32x32x16_bf16 v[48:63], v[178:181], v[234:237], v[48:63]
	ds_read_b64_tr_b16 v[234:235], v199 offset:0x3400
	ds_read_b64_tr_b16 v[236:237], v199 offset:0x3c00
	s_waitcnt lgkmcnt(0)
	v_mfma_f32_32x32x16_bf16 v[32:47], v[160:163], v[182:185], v[32:47]
	ds_read_b64_tr_b16 v[182:183], v199 offset:0x600
	ds_read_b64_tr_b16 v[184:185], v199 offset:0xe00
	v_mfma_f32_32x32x16_bf16 v[32:47], v[164:167], v[216:219], v[32:47]
	ds_read_b64_tr_b16 v[216:217], v199 offset:0x1600
	ds_read_b64_tr_b16 v[218:219], v199 offset:0x1e00
	v_mfma_f32_32x32x16_bf16 v[32:47], v[170:173], v[230:233], v[32:47]
	ds_read_b64_tr_b16 v[230:231], v199 offset:0x2600
	ds_read_b64_tr_b16 v[232:233], v199 offset:0x2e00
	v_mfma_f32_32x32x16_bf16 v[32:47], v[178:181], v[234:237], v[32:47]
	ds_read_b64_tr_b16 v[234:235], v199 offset:0x3600
	ds_read_b64_tr_b16 v[236:237], v199 offset:0x3e00
	s_waitcnt lgkmcnt(0)
	v_mfma_f32_32x32x16_bf16 v[16:31], v[160:163], v[182:185], v[16:31]
	v_max_f32_e32 v160, v81, v81
	v_max_f32_e32 v161, v80, v80
	v_max_f32_e32 v160, v161, v160
	v_max3_f32 v160, v160, v82, v83
	v_max3_f32 v160, v160, v84, v85
	v_max3_f32 v160, v160, v86, v87
	v_max3_f32 v160, v160, v88, v89
	v_max3_f32 v160, v160, v90, v91
	v_max3_f32 v160, v160, v92, v93
	v_mfma_f32_32x32x16_bf16 v[16:31], v[164:167], v[216:219], v[16:31]
	v_max3_f32 v160, v160, v94, v95
	v_max3_f32 v160, v160, v64, v65
	v_max3_f32 v160, v160, v66, v67
	v_max3_f32 v160, v160, v68, v69
	v_max3_f32 v160, v160, v70, v71
	v_max3_f32 v160, v160, v72, v73
	v_max3_f32 v160, v160, v74, v75
	v_max3_f32 v160, v160, v76, v77
	v_mfma_f32_32x32x16_bf16 v[16:31], v[170:173], v[230:233], v[16:31]
	v_max3_f32 v160, v160, v78, v79
	v_mov_b32_e32 v161, v160
	s_nop 1
	v_permlane32_swap_b32_e32 v160, v161
	v_max_f32_e32 v161, v161, v161
	v_max_f32_e32 v160, v160, v160
	v_max_f32_e32 v160, v160, v161
	v_sub_f32_e32 v161, v160, v168
	v_cmp_ge_f32_e32 vcc, s14, v161
	v_max_f32_e32 v161, v168, v168
	v_max_f32_e32 v160, v161, v160
	v_mfma_f32_32x32x16_bf16 v[16:31], v[178:181], v[234:237], v[16:31]
	v_sub_f32_e32 v161, v168, v160
	v_mul_f32_e32 v161, 0x3e0293ee, v161
	v_exp_f32_e32 v161, v161
	s_cmp_eq_u64 vcc, exec
	s_cselect_b64 s[4:5], -1, 0
	s_barrier
	s_waitcnt vmcnt(4)
	v_cndmask_b32_e64 v215, v161, 1.0, s[4:5]
	v_cmp_gt_f32_e32 vcc, 1.0, v215
	s_waitcnt vmcnt(4)
	ds_write_b128 v200, v[128:131]
	ds_write_b128 v201, v[132:135]
	ds_write_b128 v202, v[136:139] offset:32768
	ds_write_b128 v203, v[140:143] offset:32768
	s_cbranch_vccz .LBB0_713
	s_and_saveexec_b64 s[18:19], s[2:3]
	ds_write_b32 v189, v215 offset:128
	s_or_b64 exec, exec, s[18:19]
	s_waitcnt lgkmcnt(0)
	v_add_u32_e32 v161, v191, v190
	ds_read_b128 v[162:165], v161 offset:224
	ds_read_b128 v[170:173], v161 offset:192
	ds_read_b128 v[178:181], v161 offset:160
	ds_read_b128 v[182:185], v161 offset:128
	s_waitcnt lgkmcnt(3)
	v_pk_mul_f32 v[12:13], v[12:13], v[162:163]
	s_waitcnt lgkmcnt(2)
	v_pk_mul_f32 v[8:9], v[8:9], v[170:171]
	s_waitcnt lgkmcnt(1)
	v_pk_mul_f32 v[4:5], v[4:5], v[178:179]
	v_pk_mul_f32 v[14:15], v[14:15], v[164:165]
	v_pk_mul_f32 v[10:11], v[10:11], v[172:173]
	v_pk_mul_f32 v[6:7], v[6:7], v[180:181]
	s_waitcnt lgkmcnt(0)
	v_pk_mul_f32 v[2:3], v[2:3], v[184:185]
	v_pk_mul_f32 v[0:1], v[0:1], v[182:183]
	v_pk_mul_f32 v[60:61], v[60:61], v[162:163]
	v_pk_mul_f32 v[56:57], v[56:57], v[170:171]
	v_pk_mul_f32 v[52:53], v[52:53], v[178:179]
	v_pk_mul_f32 v[62:63], v[62:63], v[164:165]
	v_pk_mul_f32 v[58:59], v[58:59], v[172:173]
	v_pk_mul_f32 v[54:55], v[54:55], v[180:181]
	v_pk_mul_f32 v[50:51], v[50:51], v[184:185]
	v_pk_mul_f32 v[48:49], v[48:49], v[182:183]
	v_pk_mul_f32 v[44:45], v[44:45], v[162:163]
	v_pk_mul_f32 v[40:41], v[40:41], v[170:171]
	v_pk_mul_f32 v[36:37], v[36:37], v[178:179]
	v_pk_mul_f32 v[46:47], v[46:47], v[164:165]
	v_pk_mul_f32 v[42:43], v[42:43], v[172:173]
	v_pk_mul_f32 v[38:39], v[38:39], v[180:181]
	v_pk_mul_f32 v[34:35], v[34:35], v[184:185]
	v_pk_mul_f32 v[32:33], v[32:33], v[182:183]
	v_pk_mul_f32 v[28:29], v[28:29], v[162:163]
	v_pk_mul_f32 v[24:25], v[24:25], v[170:171]
	v_pk_mul_f32 v[20:21], v[20:21], v[178:179]
	v_pk_mul_f32 v[30:31], v[30:31], v[164:165]
	v_pk_mul_f32 v[26:27], v[26:27], v[172:173]
	v_pk_mul_f32 v[22:23], v[22:23], v[180:181]
	v_pk_mul_f32 v[18:19], v[18:19], v[184:185]
	v_pk_mul_f32 v[16:17], v[16:17], v[182:183]
.LBB0_713:
	v_cndmask_b32_e64 v216, v160, v168, s[4:5]
	v_mul_f32_e32 v217, 0xbe0293ee, v216
	v_fmamk_f32 v80, v80, 0x3e0293ee, v217
	v_fmamk_f32 v81, v81, 0x3e0293ee, v217
	v_fmamk_f32 v82, v82, 0x3e0293ee, v217
	v_fmamk_f32 v83, v83, 0x3e0293ee, v217
	v_fmamk_f32 v84, v84, 0x3e0293ee, v217
	v_fmamk_f32 v85, v85, 0x3e0293ee, v217
	v_fmamk_f32 v86, v86, 0x3e0293ee, v217
	v_fmamk_f32 v87, v87, 0x3e0293ee, v217
	v_fmamk_f32 v88, v88, 0x3e0293ee, v217
	v_fmamk_f32 v89, v89, 0x3e0293ee, v217
	v_fmamk_f32 v90, v90, 0x3e0293ee, v217
	v_fmamk_f32 v91, v91, 0x3e0293ee, v217
	v_fmamk_f32 v92, v92, 0x3e0293ee, v217
	v_fmamk_f32 v93, v93, 0x3e0293ee, v217
	v_fmamk_f32 v94, v94, 0x3e0293ee, v217
	v_fmamk_f32 v95, v95, 0x3e0293ee, v217
	v_exp_f32_e32 v160, v80
	v_exp_f32_e32 v175, v81
	v_exp_f32_e32 v161, v82
	v_exp_f32_e32 v174, v83
	v_exp_f32_e32 v162, v84
	v_exp_f32_e32 v173, v85
	v_exp_f32_e32 v163, v86
	v_exp_f32_e32 v172, v87
	v_exp_f32_e32 v164, v88
	v_exp_f32_e32 v171, v89
	v_exp_f32_e32 v165, v90
	v_exp_f32_e32 v170, v91
	v_exp_f32_e32 v166, v92
	v_exp_f32_e32 v169, v93
	v_exp_f32_e32 v167, v94
	v_exp_f32_e32 v168, v95
	v_fmamk_f32 v236, v64, 0x3e0293ee, v217
	v_fmamk_f32 v237, v65, 0x3e0293ee, v217
	v_fmamk_f32 v238, v66, 0x3e0293ee, v217
	v_fmamk_f32 v239, v67, 0x3e0293ee, v217
	v_fmamk_f32 v240, v68, 0x3e0293ee, v217
	v_fmamk_f32 v219, v69, 0x3e0293ee, v217
	v_fmamk_f32 v230, v70, 0x3e0293ee, v217
	v_fmamk_f32 v231, v71, 0x3e0293ee, v217
	v_fmamk_f32 v232, v72, 0x3e0293ee, v217
	v_fmamk_f32 v233, v73, 0x3e0293ee, v217
	v_fmamk_f32 v234, v74, 0x3e0293ee, v217
	v_fmamk_f32 v235, v75, 0x3e0293ee, v217
	v_fmamk_f32 v218, v76, 0x3e0293ee, v217
	v_fmamk_f32 v241, v77, 0x3e0293ee, v217
	v_fmamk_f32 v242, v78, 0x3e0293ee, v217
	v_fmac_f32_e32 v217, 0x3e0293ee, v79
	s_waitcnt lgkmcnt(0)
	s_barrier
	ds_read_b128 v[64:67], v204 offset:32768
	ds_read_b128 v[68:71], v204 offset:40960
	ds_read_b128 v[178:181], v207 offset:32768
	ds_read_b128 v[182:185], v207 offset:40960
	s_waitcnt lgkmcnt(3)
	v_mfma_f32_32x32x16_bf16 v[80:95], v[64:67], v[124:127], 0
	v_exp_f32_e32 v186, v232
	v_exp_f32_e32 v232, v217
	v_add_f32_e32 v217, 0, v160
	v_add_f32_e32 v217, v175, v217
	v_add_f32_e32 v217, v161, v217
	s_waitcnt lgkmcnt(2)
	v_mfma_f32_32x32x16_bf16 v[64:79], v[68:71], v[124:127], 0
	v_add_f32_e32 v217, v174, v217
	v_add_f32_e32 v217, v162, v217
	v_add_f32_e32 v217, v173, v217
	v_add_f32_e32 v217, v163, v217
	v_add_f32_e32 v217, v172, v217
	s_waitcnt lgkmcnt(1)
	v_mfma_f32_32x32x16_bf16 v[80:95], v[178:181], v[120:123], v[80:95]
	v_add_f32_e32 v217, v164, v217
	v_add_f32_e32 v217, v171, v217
	v_add_f32_e32 v217, v165, v217
	v_add_f32_e32 v217, v170, v217
	v_add_f32_e32 v217, v166, v217
	s_waitcnt lgkmcnt(0)
	v_mfma_f32_32x32x16_bf16 v[64:79], v[182:185], v[120:123], v[64:79]
	v_add_f32_e32 v217, v169, v217
	v_add_f32_e32 v217, v167, v217
	v_add_f32_e32 v217, v168, v217
	v_exp_f32_e32 v187, v233
	v_exp_f32_e32 v224, v235
	ds_read_b128 v[178:181], v209 offset:32768
	ds_read_b128 v[182:185], v209 offset:40960
	s_waitcnt lgkmcnt(1)
	v_mfma_f32_32x32x16_bf16 v[80:95], v[178:181], v[116:119], v[80:95]
	v_exp_f32_e32 v225, v218
	v_cvt_pk_bf16_f32 v160, v160, v175
	v_cvt_pk_bf16_f32 v161, v161, v174
	v_cvt_pk_bf16_f32 v162, v162, v173
	v_cvt_pk_bf16_f32 v163, v163, v172
	s_waitcnt lgkmcnt(0)
	v_mfma_f32_32x32x16_bf16 v[64:79], v[182:185], v[116:119], v[64:79]
	v_cvt_pk_bf16_f32 v164, v164, v171
	v_cvt_pk_bf16_f32 v165, v165, v170
	v_cvt_pk_bf16_f32 v166, v166, v169
	v_cvt_pk_bf16_f32 v167, v167, v168
	v_cvt_pk_bf16_f32 v172, v186, v187
	ds_read_b128 v[178:181], v205 offset:32768
	ds_read_b128 v[182:185], v205 offset:40960
	s_waitcnt lgkmcnt(1)
	v_mfma_f32_32x32x16_bf16 v[80:95], v[178:181], v[112:115], v[80:95]
	v_permlane32_swap_b32_e32 v160, v162
	v_permlane32_swap_b32_e32 v161, v163
	v_permlane32_swap_b32_e32 v164, v166
	v_permlane32_swap_b32_e32 v165, v167
	s_waitcnt lgkmcnt(0)
	v_mfma_f32_32x32x16_bf16 v[64:79], v[182:185], v[112:115], v[64:79]
	ds_read_b128 v[178:181], v206 offset:32768
	ds_read_b128 v[182:185], v206 offset:40960
	s_waitcnt lgkmcnt(1)
	v_mfma_f32_32x32x16_bf16 v[80:95], v[178:181], v[108:111], v[80:95]
	s_waitcnt lgkmcnt(0)
	v_mfma_f32_32x32x16_bf16 v[64:79], v[182:185], v[108:111], v[64:79]
	ds_read_b128 v[178:181], v208 offset:32768
	ds_read_b128 v[182:185], v208 offset:40960
	s_waitcnt lgkmcnt(1)
	v_mfma_f32_32x32x16_bf16 v[80:95], v[178:181], v[104:107], v[80:95]
	s_waitcnt lgkmcnt(0)
	v_mfma_f32_32x32x16_bf16 v[64:79], v[182:185], v[104:107], v[64:79]
	ds_read_b128 v[178:181], v210 offset:32768
	ds_read_b128 v[182:185], v210 offset:40960
	s_waitcnt lgkmcnt(1)
	v_mfma_f32_32x32x16_bf16 v[80:95], v[178:181], v[100:103], v[80:95]
	s_waitcnt lgkmcnt(0)
	v_mfma_f32_32x32x16_bf16 v[64:79], v[182:185], v[100:103], v[64:79]
	ds_read_b128 v[178:181], v211 offset:32768
	ds_read_b128 v[182:185], v211 offset:40960
	s_waitcnt lgkmcnt(1)
	v_mfma_f32_32x32x16_bf16 v[80:95], v[178:181], v[96:99], v[80:95]
	v_exp_f32_e32 v178, v236
	v_exp_f32_e32 v179, v237
	v_add_f32_e32 v217, v178, v217
	v_add_f32_e32 v217, v179, v217
	v_cvt_pk_bf16_f32 v168, v178, v179
	s_waitcnt lgkmcnt(0)
	v_mfma_f32_32x32x16_bf16 v[64:79], v[182:185], v[96:99], v[64:79]
	v_exp_f32_e32 v180, v238
	v_exp_f32_e32 v181, v239
	v_add_f32_e32 v217, v180, v217
	v_add_f32_e32 v217, v181, v217
	v_cvt_pk_bf16_f32 v169, v180, v181
	v_exp_f32_e32 v182, v240
	v_exp_f32_e32 v183, v219
	v_exp_f32_e32 v184, v230
	v_exp_f32_e32 v185, v231
	v_add_f32_e32 v217, v182, v217
	v_add_f32_e32 v217, v183, v217
	v_exp_f32_e32 v219, v234
	v_add_f32_e32 v217, v184, v217
	v_add_f32_e32 v217, v185, v217
	v_add_f32_e32 v217, v186, v217
	v_exp_f32_e32 v230, v241
	v_add_f32_e32 v217, v187, v217
	v_exp_f32_e32 v231, v242
	v_add_f32_e32 v217, v219, v217
	v_add_f32_e32 v217, v224, v217
	v_add_f32_e32 v217, v225, v217
	v_add_f32_e32 v217, v230, v217
	v_add_f32_e32 v217, v231, v217
	v_add_f32_e32 v217, v232, v217
	v_mov_b32_e32 v218, v217
	v_cvt_pk_bf16_f32 v170, v182, v183
	v_cvt_pk_bf16_f32 v171, v184, v185
	v_cvt_pk_bf16_f32 v173, v219, v224
	v_cvt_pk_bf16_f32 v174, v225, v230
	v_cvt_pk_bf16_f32 v175, v231, v232
	v_permlane32_swap_b32_e32 v217, v218
	v_permlane32_swap_b32_e32 v168, v170
	v_permlane32_swap_b32_e32 v169, v171
	v_permlane32_swap_b32_e32 v172, v174
	v_permlane32_swap_b32_e32 v173, v175
	s_cmpk_gt_u32 s20, 0x44
	s_cbranch_scc1 .LBB0_715
	s_cmp_lt_u32 s20, 5
	s_cselect_b64 s[4:5], -1, 0
	s_and_b64 s[18:19], s[4:5], exec
	s_cselect_b32 s16, 0, -8
	s_add_i32 s16, s16, s85
	s_and_b64 s[4:5], s[4:5], exec
	s_cselect_b32 s19, s49, s43
	s_cselect_b32 s18, s48, s36
	s_cselect_b32 s21, s57, s52
	s_cselect_b32 s22, s56, s44
	s_lshl_b64 s[4:5], s[16:17], 16
	s_add_u32 s18, s18, s4
	s_addc_u32 s19, s19, s5
	s_add_u32 s4, s22, s4
	s_addc_u32 s5, s21, s5
	global_load_dwordx4 v[128:131], v222, s[4:5]
	global_load_dwordx4 v[132:135], v243, s[4:5]
	global_load_dwordx4 v[136:139], v222, s[18:19]
	global_load_dwordx4 v[140:143], v243, s[18:19]
